# plus XCD-aware tile order for the MLA in-projection GEMM
# baseline (speedup 1.0000x reference)
;     ...
;   for (int tile = t_start; tile < t_total; tile += t_step) {
;     int mt, nt;
;     if (cntS) { mt = tile / cntS; nt = xi + 8 * (tile % cntS); } else { mt = tile / Ntiles; nt = tile % Ntiles; }
;     const int m0 = mt * 128, n0 = nt * 128;
.LBB0_227:
	s_cmp_lg_u32 s26, 0x200
	s_cbranch_scc1 .Lmy_xr_plain_mi
	s_and_b32 s14, s56, 7
	s_bfe_u32 s5, s56, 0x60003
	s_lshr_b32 s0, s56, 9
	s_lshl_b32 s0, s0, 6
	s_add_i32 s5, s5, s0
	s_mul_i32 s0, s5, 43
	s_lshr_b32 s0, s0, 8
	s_mul_i32 s4, s0, 6
	s_sub_i32 s4, s5, s4
	s_lshl_b32 s0, s0, 3
	s_add_i32 s5, s14, s0
	s_mov_b32 s14, s4
	s_branch .Lmy_xr_join_mi

; DI int opaque_tid() { int t = threadIdx.x; asm volatile("" : "+v"(t)); return t; }
; DI void gemm_mainloop(const bf16* __restrict__ A, int lda, const bf16* __restrict__ Bt, int ldb, int K, int m0, int n0,
;                       bf16* As, bf16* Bs, f32x16& acc0, f32x16& acc1, f32x16& acc2, f32x16& acc3) {
;   const int tid = opaque_tid(), lane = tid & 63, w = tid >> 6, r = lane & 31, g = lane >> 5;
;   const int lrow = tid >> 3, lcc = (tid & 7) * 8;
;   const bf16* ap = A + (size_t)(m0 + lrow) * lda + lcc;
;   const bf16* bp = Bt + (size_t)(n0 + lrow) * ldb + lcc;
;   GTile t0, t1;
;   asm volatile("" ::: "memory");
;   const int nkt = K >> 6;
;   int kb = ((((m0 >> 7) * 5 + (n0 >> 7) * 3) >> 1) % nkt) << 6;
;     ...
;   gt_load(t0, ap, bp, lda, ldb, KW(0));
;   gt_load(t1, ap, bp, lda, ldb, KW(64));
; #pragma unroll
;   for (int i = 0; i < 16; ++i) { acc0[i] = 0.f; acc1[i] = 0.f; acc2[i] = 0.f; acc3[i] = 0.f; }
;   bf16* asw = As + lrow * LDT + lcc;
;   bf16* bsw = Bs + lrow * LDT + lcc;
;   const bf16* asr = As + (32 * w + r) * LDT + g * 8;
;   const bf16* bsr = Bs + r * LDT + g * 8;
.Lmy_xr_join_mi:
	v_mov_b32_e32 v8, v160
	s_mul_i32 s0, s5, 5
	s_mul_i32 s1, s14, 3
	s_lshl_b32 s4, s5, 7
	s_add_i32 s1, s1, s0
	v_ashrrev_i32_e32 v9, 3, v8
	v_add_u32_e32 v0, s4, v9
	s_ashr_i32 s0, s1, 1
	s_ashr_i32 s1, s1, 31
	s_waitcnt lgkmcnt(0)
	v_ashrrev_i32_e32 v1, 31, v0
	s_lshr_b32 s1, s1, 28
	v_lshlrev_b64 v[0:1], 11, v[0:1]
	v_lshlrev_b32_e32 v2, 4, v8
	s_add_i32 s1, s0, s1
	s_lshl_b32 s16, s14, 7
	v_lshl_add_u64 v[0:1], s[36:37], 0, v[0:1]
	v_and_b32_e32 v130, 0x70, v2
	s_and_b32 s1, s1, -16
	v_lshl_add_u64 v[136:137], v[0:1], 0, v[130:131]
	v_add_u32_e32 v0, s16, v9
	s_sub_i32 s15, s0, s1
	v_ashrrev_i32_e32 v1, 31, v0
	s_lshl_b32 s18, s15, 6
	v_lshlrev_b64 v[0:1], 11, v[0:1]
	s_ashr_i32 s19, s18, 31
	v_lshl_add_u64 v[0:1], s[8:9], 0, v[0:1]
	s_lshl_b64 s[0:1], s[18:19], 1
	v_lshl_add_u64 v[138:139], v[0:1], 0, v[130:131]
	v_lshl_add_u64 v[0:1], v[136:137], 0, s[0:1]
	v_add_co_u32_e32 v4, vcc, s48, v0
	v_lshl_add_u64 v[2:3], v[138:139], 0, s[0:1]
	s_nop 0
	v_addc_co_u32_e32 v5, vcc, 0, v1, vcc
	v_add_co_u32_e32 v6, vcc, s49, v0
	s_cmp_lt_i32 s15, 15
	s_nop 0
	v_addc_co_u32_e32 v7, vcc, 0, v1, vcc
	global_load_dwordx4 v[64:67], v[4:5], off
	global_load_dwordx4 v[68:71], v[6:7], off
	v_add_co_u32_e32 v4, vcc, s50, v0
	global_load_dwordx4 v[72:75], v[0:1], off
	global_load_dwordx4 v[76:79], v[2:3], off
	v_addc_co_u32_e32 v5, vcc, 0, v1, vcc
	v_add_co_u32_e32 v6, vcc, s48, v2
	s_cselect_b32 s1, 0, -1
	s_nop 0
	v_addc_co_u32_e32 v7, vcc, 0, v3, vcc
	global_load_dwordx4 v[80:83], v[4:5], off
	global_load_dwordx4 v[84:87], v[6:7], off
	v_add_co_u32_e32 v4, vcc, s49, v2
	s_cselect_b32 s0, 0, 0xfffff800
	s_nop 0
	v_addc_co_u32_e32 v5, vcc, 0, v3, vcc
	v_add_co_u32_e32 v6, vcc, s50, v2
	v_lshl_add_u64 v[0:1], v[0:1], 0, s[0:1]
	s_nop 0
	v_addc_co_u32_e32 v7, vcc, 0, v3, vcc
	global_load_dwordx4 v[96:99], v[4:5], off
	global_load_dwordx4 v[100:103], v[6:7], off
	v_add_co_u32_e32 v4, vcc, s48, v0
	v_lshl_add_u64 v[2:3], v[2:3], 0, s[0:1]
	s_nop 0
	v_addc_co_u32_e32 v5, vcc, 0, v1, vcc
	v_add_co_u32_e32 v6, vcc, s49, v0
	v_mad_u64_u32 v[140:141], s[0:1], v9, s51, v[130:131]
	s_nop 0
	v_addc_co_u32_e32 v7, vcc, 0, v1, vcc
	global_load_dwordx4 v[88:91], v[4:5], off offset:128
	global_load_dwordx4 v[92:95], v[6:7], off offset:128
	v_add_co_u32_e32 v4, vcc, s50, v0
	global_load_dwordx4 v[104:107], v[0:1], off offset:128
	global_load_dwordx4 v[108:111], v[2:3], off offset:128
	v_addc_co_u32_e32 v5, vcc, 0, v1, vcc
	v_add_co_u32_e32 v0, vcc, s48, v2
	s_sub_i32 s15, 0x400, s18
	s_nop 0
	v_addc_co_u32_e32 v1, vcc, 0, v3, vcc
	global_load_dwordx4 v[112:115], v[4:5], off offset:128
	global_load_dwordx4 v[116:119], v[0:1], off offset:128
	v_add_co_u32_e32 v0, vcc, s49, v2
	s_sub_i32 s17, 0x340, s18
	s_nop 0
	v_addc_co_u32_e32 v1, vcc, 0, v3, vcc
	v_add_co_u32_e32 v2, vcc, s50, v2
	s_mov_b64 s[20:21], 0
	s_nop 0
	v_addc_co_u32_e32 v3, vcc, 0, v3, vcc
	global_load_dwordx4 v[120:123], v[0:1], off offset:128
	global_load_dwordx4 v[124:127], v[2:3], off offset:128
	v_and_b32_e32 v1, 31, v8
	v_lshrrev_b32_e32 v0, 1, v8
	v_and_or_b32 v2, v0, s52, v1
	v_and_b32_e32 v0, 16, v0
	v_mad_u64_u32 v[142:143], s[0:1], v2, s51, v[0:1]
	v_mad_u32_u24 v130, v1, s51, v0
	v_mov_b32_e32 v0, 0
	v_mov_b32_e32 v1, v131
	v_mov_b32_e32 v2, v131
	v_mov_b32_e32 v3, v131
	v_mov_b32_e32 v4, v131
	v_mov_b32_e32 v5, v131
	v_mov_b32_e32 v6, v131
	v_mov_b32_e32 v7, v131
	v_mov_b32_e32 v8, v131
	v_mov_b32_e32 v9, v131
	v_mov_b32_e32 v10, v131
	v_mov_b32_e32 v11, v131
	v_mov_b32_e32 v12, v131
	v_mov_b32_e32 v13, v131
	v_mov_b32_e32 v14, v131
	v_mov_b32_e32 v15, v131
	v_mov_b32_e32 v16, 0
	v_mov_b32_e32 v17, v131
	v_mov_b32_e32 v18, v131
	v_mov_b32_e32 v19, v131
	v_mov_b32_e32 v20, v131
	v_mov_b32_e32 v21, v131
	v_mov_b32_e32 v22, v131
	v_mov_b32_e32 v23, v131
	v_mov_b32_e32 v24, v131
	v_mov_b32_e32 v25, v131
	v_mov_b32_e32 v26, v131
	v_mov_b32_e32 v27, v131
	v_mov_b32_e32 v28, v131
	v_mov_b32_e32 v29, v131
	v_mov_b32_e32 v30, v131
	v_mov_b32_e32 v31, v131
	v_mov_b32_e32 v32, 0
	v_mov_b32_e32 v33, v131
	v_mov_b32_e32 v34, v131
	v_mov_b32_e32 v35, v131
	v_mov_b32_e32 v36, v131
	v_mov_b32_e32 v37, v131
	v_mov_b32_e32 v38, v131
	v_mov_b32_e32 v39, v131
	v_mov_b32_e32 v40, v131
	v_mov_b32_e32 v41, v131
	v_mov_b32_e32 v42, v131
	v_mov_b32_e32 v43, v131
	v_mov_b32_e32 v44, v131
	v_mov_b32_e32 v45, v131
	v_mov_b32_e32 v46, v131
	v_mov_b32_e32 v47, v131
	v_mov_b32_e32 v48, 0
	v_mov_b32_e32 v49, v131
	v_mov_b32_e32 v50, v131
	v_mov_b32_e32 v51, v131
	v_mov_b32_e32 v52, v131
	v_mov_b32_e32 v53, v131
	v_mov_b32_e32 v54, v131
	v_mov_b32_e32 v55, v131
	v_mov_b32_e32 v56, v131
	v_mov_b32_e32 v57, v131
	v_mov_b32_e32 v58, v131
	v_mov_b32_e32 v59, v131
	v_mov_b32_e32 v60, v131
	v_mov_b32_e32 v61, v131
	v_mov_b32_e32 v62, v131
	v_mov_b32_e32 v63, v131
	s_branch .LBB0_229
